# stack: back-edge rotation of the three K-loops plus per-unit LDS read bases in the out-projection loop
# baseline (speedup 1.0000x reference)
.LBB0_639:
	v_add_u32_e32 v250, s71, v139
	v_add_u32_e32 v251, s72, v139
	v_add_u32_e32 v252, s79, v139
	v_add_u32_e32 v253, 0x1c000, v139
	s_mov_b64 s[34:35], s[8:9]
	s_add_u32 s83, s34, 0x100
	s_addc_u32 s84, s35, 0
	v_add_co_u32_e64 v56, s[26:27], s80, 1
	s_and_b64 s[8:9], s[26:27], exec
	s_cselect_b32 s10, s4, s69
	s_cselect_b32 s82, s66, 0
	s_cmp_gt_i32 s80, 0
	s_cselect_b64 s[20:21], -1, 0
	s_ashr_i32 s11, s10, 31
	s_lshl_b64 s[8:9], s[10:11], 21
	s_add_u32 s3, s56, s8
	s_addc_u32 s8, s57, s9
	s_lshl_b32 s9, s82, 1
	s_add_u32 s24, s3, s9
	s_addc_u32 s25, s8, 0
	s_add_u32 s8, s42, s9
	s_addc_u32 s9, s43, 0
	s_cmp_lt_i32 s80, 1
	s_cselect_b64 s[28:29], -1, 0
	s_and_b64 s[36:37], s[28:29], exec
	s_cselect_b32 s11, s25, s23
	s_cselect_b32 s85, s24, s22
	s_cselect_b32 s86, s9, s35
	s_cselect_b32 s87, s8, s34
	s_lshl_b32 s3, s49, 7
	s_addk_i32 s3, 0xfc00
	v_readfirstlane_b32 s81, v56
	v_lshl_add_u64 v[58:59], s[22:23], 0, v[142:143]
	v_lshl_add_u64 v[146:147], s[22:23], 0, v[144:145]
	s_add_u32 s88, s3, 0x300
	s_mov_b64 s[34:35], 0
	s_mov_b32 s89, 0
	s_add_i32 s89, s89, 2
	s_add_u32 s3, s22, s34
	ds_read_b128 v[150:153], v250
	ds_read_b128 v[154:157], v250 offset:1024
	ds_read_b128 v[158:161], v250 offset:2048
	ds_read_b128 v[162:165], v250 offset:3072
	s_addc_u32 s36, s23, s35
	s_add_u32 s3, s3, 0x100
	s_addc_u32 s36, s36, 0
	s_add_u32 s90, s83, s34
	s_addc_u32 s37, s84, s35
	s_cmp_eq_u32 s88, s34
	s_cselect_b32 s39, s11, s36
	s_cselect_b32 s38, s85, s3
	s_cselect_b32 s37, s86, s37
	s_cselect_b32 s36, s87, s90
	s_mov_b32 m0, s73
	v_lshl_add_u64 v[174:175], v[58:59], 0, s[34:35]
	ds_read_b128 v[166:169], v133
	ds_read_b128 v[170:173], v133 offset:1024
	ds_read_b128 v[182:185], v133 offset:2048
	ds_read_b128 v[186:189], v133 offset:3072
	ds_read_b128 v[190:193], v133 offset:4096
	ds_read_b128 v[194:197], v133 offset:5120
	ds_read_b128 v[198:201], v133 offset:6144
	ds_read_b128 v[202:205], v133 offset:7168
	global_load_lds_dwordx4 v[174:175], off
	s_mov_b32 m0, s74
	v_lshl_add_u64 v[174:175], v[146:147], 0, s[34:35]
	global_load_lds_dwordx4 v[174:175], off
	s_waitcnt lgkmcnt(8)
	s_barrier
	s_waitcnt lgkmcnt(0)
	v_mfma_f32_16x16x32_bf16 v[128:131], v[150:153], v[166:169], 0
	v_mfma_f32_16x16x32_bf16 v[124:127], v[158:161], v[166:169], 0
	v_mfma_f32_16x16x32_bf16 v[112:115], v[150:153], v[182:185], 0
	v_mfma_f32_16x16x32_bf16 v[108:111], v[158:161], v[182:185], 0
	v_mfma_f32_16x16x32_bf16 v[96:99], v[150:153], v[190:193], 0
	v_mfma_f32_16x16x32_bf16 v[92:95], v[158:161], v[190:193], 0
	v_mfma_f32_16x16x32_bf16 v[80:83], v[150:153], v[198:201], 0
	v_mfma_f32_16x16x32_bf16 v[76:79], v[158:161], v[198:201], 0
	v_mfma_f32_16x16x32_bf16 v[128:131], v[154:157], v[170:173], v[128:131]
	v_mfma_f32_16x16x32_bf16 v[124:127], v[162:165], v[170:173], v[124:127]
	v_mfma_f32_16x16x32_bf16 v[112:115], v[154:157], v[186:189], v[112:115]
	v_mfma_f32_16x16x32_bf16 v[108:111], v[162:165], v[186:189], v[108:111]
	v_mfma_f32_16x16x32_bf16 v[96:99], v[154:157], v[194:197], v[96:99]
	v_mfma_f32_16x16x32_bf16 v[92:95], v[162:165], v[194:197], v[92:95]
	v_mfma_f32_16x16x32_bf16 v[80:83], v[154:157], v[202:205], v[80:83]
	v_mfma_f32_16x16x32_bf16 v[76:79], v[162:165], v[202:205], v[76:79]
	s_barrier
	s_mov_b32 m0, s75
	v_lshl_add_u64 v[174:175], s[36:37], 0, v[134:135]
	ds_read_b128 v[206:209], v251
	ds_read_b128 v[214:217], v251 offset:1024
	ds_read_b128 v[218:221], v251 offset:2048
	ds_read_b128 v[222:225], v251 offset:3072
	global_load_lds_dwordx4 v[174:175], off
	s_mov_b32 m0, s76
	v_lshl_add_u64 v[226:227], s[36:37], 0, v[136:137]
	global_load_lds_dwordx4 v[226:227], off
	s_barrier
	s_waitcnt lgkmcnt(0)
	v_mfma_f32_16x16x32_bf16 v[120:123], v[206:209], v[166:169], 0
	v_mfma_f32_16x16x32_bf16 v[116:119], v[218:221], v[166:169], 0
	v_mfma_f32_16x16x32_bf16 v[104:107], v[206:209], v[182:185], 0
	v_mfma_f32_16x16x32_bf16 v[100:103], v[218:221], v[182:185], 0
	v_mfma_f32_16x16x32_bf16 v[88:91], v[206:209], v[190:193], 0
	v_mfma_f32_16x16x32_bf16 v[84:87], v[218:221], v[190:193], 0
	v_mfma_f32_16x16x32_bf16 v[72:75], v[206:209], v[198:201], 0
	v_mfma_f32_16x16x32_bf16 v[68:71], v[218:221], v[198:201], 0
	v_mfma_f32_16x16x32_bf16 v[120:123], v[214:217], v[170:173], v[120:123]
	v_mfma_f32_16x16x32_bf16 v[116:119], v[222:225], v[170:173], v[116:119]
	v_mfma_f32_16x16x32_bf16 v[104:107], v[214:217], v[186:189], v[104:107]
	v_mfma_f32_16x16x32_bf16 v[100:103], v[222:225], v[186:189], v[100:103]
	v_mfma_f32_16x16x32_bf16 v[88:91], v[214:217], v[194:197], v[88:91]
	v_mfma_f32_16x16x32_bf16 v[84:87], v[222:225], v[194:197], v[84:87]
	v_mfma_f32_16x16x32_bf16 v[72:75], v[214:217], v[202:205], v[72:75]
	v_mfma_f32_16x16x32_bf16 v[68:71], v[222:225], v[202:205], v[68:71]
	s_mov_b32 m0, s44
	v_lshl_add_u64 v[228:229], s[38:39], 0, v[134:135]
	s_barrier
	ds_read_b128 v[166:169], v133 offset:16384
	ds_read_b128 v[170:173], v133 offset:17408
	ds_read_b128 v[182:185], v133 offset:18432
	ds_read_b128 v[186:189], v133 offset:19456
	ds_read_b128 v[190:193], v133 offset:20480
	ds_read_b128 v[194:197], v133 offset:21504
	ds_read_b128 v[198:201], v133 offset:22528
	ds_read_b128 v[202:205], v133 offset:23552
	global_load_lds_dwordx4 v[228:229], off
	s_mov_b32 m0, s45
	v_lshl_add_u64 v[230:231], s[38:39], 0, v[136:137]
	global_load_lds_dwordx4 v[230:231], off
	s_barrier
	s_waitcnt lgkmcnt(0)
	v_mfma_f32_16x16x32_bf16 v[64:67], v[150:153], v[166:169], 0
	v_mfma_f32_16x16x32_bf16 v[60:63], v[158:161], v[166:169], 0
	v_mfma_f32_16x16x32_bf16 v[44:47], v[150:153], v[182:185], 0
	v_mfma_f32_16x16x32_bf16 v[40:43], v[158:161], v[182:185], 0
	v_mfma_f32_16x16x32_bf16 v[28:31], v[150:153], v[190:193], 0
	v_mfma_f32_16x16x32_bf16 v[24:27], v[158:161], v[190:193], 0
	v_mfma_f32_16x16x32_bf16 v[12:15], v[150:153], v[198:201], 0
	v_mfma_f32_16x16x32_bf16 v[8:11], v[158:161], v[198:201], 0
	v_mfma_f32_16x16x32_bf16 v[64:67], v[154:157], v[170:173], v[64:67]
	v_mfma_f32_16x16x32_bf16 v[60:63], v[162:165], v[170:173], v[60:63]
	v_mfma_f32_16x16x32_bf16 v[44:47], v[154:157], v[186:189], v[44:47]
	v_mfma_f32_16x16x32_bf16 v[40:43], v[162:165], v[186:189], v[40:43]
	v_mfma_f32_16x16x32_bf16 v[28:31], v[154:157], v[194:197], v[28:31]
	v_mfma_f32_16x16x32_bf16 v[24:27], v[162:165], v[194:197], v[24:27]
	v_mfma_f32_16x16x32_bf16 v[12:15], v[154:157], v[202:205], v[12:15]
	v_mfma_f32_16x16x32_bf16 v[8:11], v[162:165], v[202:205], v[8:11]
	s_barrier
	s_add_u32 s90, s36, 0x100000
	s_addc_u32 s91, s37, 0
	s_mov_b32 m0, s77
	v_lshl_add_u64 v[150:151], s[90:91], 0, v[134:135]
	global_load_lds_dwordx4 v[150:151], off
	s_mov_b32 m0, s78
	v_lshl_add_u64 v[150:151], s[90:91], 0, v[136:137]
	global_load_lds_dwordx4 v[150:151], off
	s_waitcnt vmcnt(6)
	s_barrier
	v_mfma_f32_16x16x32_bf16 v[52:55], v[206:209], v[166:169], 0
	v_mfma_f32_16x16x32_bf16 v[48:51], v[218:221], v[166:169], 0
	v_mfma_f32_16x16x32_bf16 v[36:39], v[206:209], v[182:185], 0
	v_mfma_f32_16x16x32_bf16 v[32:35], v[218:221], v[182:185], 0
	v_mfma_f32_16x16x32_bf16 v[20:23], v[206:209], v[190:193], 0
	v_mfma_f32_16x16x32_bf16 v[16:19], v[218:221], v[190:193], 0
	v_mfma_f32_16x16x32_bf16 v[4:7], v[206:209], v[198:201], 0
	v_mfma_f32_16x16x32_bf16 v[0:3], v[218:221], v[198:201], 0
	v_mfma_f32_16x16x32_bf16 v[52:55], v[214:217], v[170:173], v[52:55]
	v_mfma_f32_16x16x32_bf16 v[48:51], v[222:225], v[170:173], v[48:51]
	v_mfma_f32_16x16x32_bf16 v[36:39], v[214:217], v[186:189], v[36:39]
	v_mfma_f32_16x16x32_bf16 v[32:35], v[222:225], v[186:189], v[32:35]
	v_mfma_f32_16x16x32_bf16 v[20:23], v[214:217], v[194:197], v[20:23]
	v_mfma_f32_16x16x32_bf16 v[16:19], v[222:225], v[194:197], v[16:19]
	v_mfma_f32_16x16x32_bf16 v[4:7], v[214:217], v[202:205], v[4:7]
	v_mfma_f32_16x16x32_bf16 v[0:3], v[222:225], v[202:205], v[0:3]
	s_barrier
	ds_read_b128 v[150:153], v252
	ds_read_b128 v[154:157], v252 offset:1024
	ds_read_b128 v[158:161], v252 offset:2048
	ds_read_b128 v[162:165], v252 offset:3072
	s_add_u32 s38, s38, 0x100000
	s_addc_u32 s39, s39, 0
	s_mov_b32 m0, s46
	v_lshl_add_u64 v[206:207], s[38:39], 0, v[134:135]
	ds_read_b128 v[166:169], v133 offset:32768
	ds_read_b128 v[170:173], v133 offset:33792
	ds_read_b128 v[182:185], v133 offset:34816
	ds_read_b128 v[186:189], v133 offset:35840
	ds_read_b128 v[190:193], v133 offset:36864
	ds_read_b128 v[194:197], v133 offset:37888
	ds_read_b128 v[198:201], v133 offset:38912
	ds_read_b128 v[202:205], v133 offset:39936
	global_load_lds_dwordx4 v[206:207], off
	s_mov_b32 m0, s47
	v_lshl_add_u64 v[206:207], s[38:39], 0, v[136:137]
	global_load_lds_dwordx4 v[206:207], off
	s_waitcnt lgkmcnt(8)
	s_barrier
	s_waitcnt lgkmcnt(0)
	v_mfma_f32_16x16x32_bf16 v[128:131], v[150:153], v[166:169], v[128:131]
	v_mfma_f32_16x16x32_bf16 v[124:127], v[158:161], v[166:169], v[124:127]
	v_mfma_f32_16x16x32_bf16 v[112:115], v[150:153], v[182:185], v[112:115]
	v_mfma_f32_16x16x32_bf16 v[108:111], v[158:161], v[182:185], v[108:111]
	v_mfma_f32_16x16x32_bf16 v[96:99], v[150:153], v[190:193], v[96:99]
	v_mfma_f32_16x16x32_bf16 v[92:95], v[158:161], v[190:193], v[92:95]
	v_mfma_f32_16x16x32_bf16 v[80:83], v[150:153], v[198:201], v[80:83]
	v_mfma_f32_16x16x32_bf16 v[76:79], v[158:161], v[198:201], v[76:79]
	v_mfma_f32_16x16x32_bf16 v[128:131], v[154:157], v[170:173], v[128:131]
	v_mfma_f32_16x16x32_bf16 v[124:127], v[162:165], v[170:173], v[124:127]
	v_mfma_f32_16x16x32_bf16 v[112:115], v[154:157], v[186:189], v[112:115]
	v_mfma_f32_16x16x32_bf16 v[108:111], v[162:165], v[186:189], v[108:111]
	v_mfma_f32_16x16x32_bf16 v[96:99], v[154:157], v[194:197], v[96:99]
	v_mfma_f32_16x16x32_bf16 v[92:95], v[162:165], v[194:197], v[92:95]
	v_mfma_f32_16x16x32_bf16 v[80:83], v[154:157], v[202:205], v[80:83]
	v_mfma_f32_16x16x32_bf16 v[76:79], v[162:165], v[202:205], v[76:79]
	s_barrier
	s_add_i32 s3, 0, 0x1c000
	s_add_i32 s38, s79, s41
	v_lshl_add_u64 v[174:175], v[174:175], 0, s[16:17]
	s_mov_b32 m0, s38
	ds_read_b128 v[206:209], v253
	ds_read_b128 v[214:217], v253 offset:1024
	ds_read_b128 v[218:221], v253 offset:2048
	ds_read_b128 v[222:225], v253 offset:3072
	global_load_lds_dwordx4 v[174:175], off
	s_add_i32 m0, s38, 0x2000
	v_lshl_add_u64 v[174:175], v[226:227], 0, s[16:17]
	global_load_lds_dwordx4 v[174:175], off
	s_barrier
	s_waitcnt lgkmcnt(0)
	v_mfma_f32_16x16x32_bf16 v[120:123], v[206:209], v[166:169], v[120:123]
	v_mfma_f32_16x16x32_bf16 v[116:119], v[218:221], v[166:169], v[116:119]
	v_mfma_f32_16x16x32_bf16 v[104:107], v[206:209], v[182:185], v[104:107]
	v_mfma_f32_16x16x32_bf16 v[100:103], v[218:221], v[182:185], v[100:103]
	v_mfma_f32_16x16x32_bf16 v[88:91], v[206:209], v[190:193], v[88:91]
	v_mfma_f32_16x16x32_bf16 v[84:87], v[218:221], v[190:193], v[84:87]
	v_mfma_f32_16x16x32_bf16 v[72:75], v[206:209], v[198:201], v[72:75]
	v_mfma_f32_16x16x32_bf16 v[68:71], v[218:221], v[198:201], v[68:71]
	v_mfma_f32_16x16x32_bf16 v[120:123], v[214:217], v[170:173], v[120:123]
	v_mfma_f32_16x16x32_bf16 v[116:119], v[222:225], v[170:173], v[116:119]
	v_mfma_f32_16x16x32_bf16 v[104:107], v[214:217], v[186:189], v[104:107]
	v_mfma_f32_16x16x32_bf16 v[100:103], v[222:225], v[186:189], v[100:103]
	v_mfma_f32_16x16x32_bf16 v[88:91], v[214:217], v[194:197], v[88:91]
	v_mfma_f32_16x16x32_bf16 v[84:87], v[222:225], v[194:197], v[84:87]
	v_mfma_f32_16x16x32_bf16 v[72:75], v[214:217], v[202:205], v[72:75]
	v_mfma_f32_16x16x32_bf16 v[68:71], v[222:225], v[202:205], v[68:71]
	s_mov_b32 m0, s67
	v_lshl_add_u64 v[174:175], v[228:229], 0, s[16:17]
	s_barrier
	ds_read_b128 v[166:169], v133 offset:49152
	ds_read_b128 v[170:173], v133 offset:50176
	ds_read_b128 v[182:185], v133 offset:51200
	ds_read_b128 v[186:189], v133 offset:52224
	ds_read_b128 v[190:193], v133 offset:53248
	ds_read_b128 v[194:197], v133 offset:54272
	ds_read_b128 v[198:201], v133 offset:55296
	ds_read_b128 v[202:205], v133 offset:56320
	global_load_lds_dwordx4 v[174:175], off
	s_mov_b32 m0, s68
	v_lshl_add_u64 v[174:175], v[230:231], 0, s[16:17]
	global_load_lds_dwordx4 v[174:175], off
	s_barrier
	s_waitcnt lgkmcnt(0)
	v_mfma_f32_16x16x32_bf16 v[64:67], v[150:153], v[166:169], v[64:67]
	v_mfma_f32_16x16x32_bf16 v[60:63], v[158:161], v[166:169], v[60:63]
	v_mfma_f32_16x16x32_bf16 v[44:47], v[150:153], v[182:185], v[44:47]
	v_mfma_f32_16x16x32_bf16 v[40:43], v[158:161], v[182:185], v[40:43]
	v_mfma_f32_16x16x32_bf16 v[28:31], v[150:153], v[190:193], v[28:31]
	v_mfma_f32_16x16x32_bf16 v[24:27], v[158:161], v[190:193], v[24:27]
	v_mfma_f32_16x16x32_bf16 v[12:15], v[150:153], v[198:201], v[12:15]
	v_mfma_f32_16x16x32_bf16 v[8:11], v[158:161], v[198:201], v[8:11]
	v_mfma_f32_16x16x32_bf16 v[64:67], v[154:157], v[170:173], v[64:67]
	v_mfma_f32_16x16x32_bf16 v[60:63], v[162:165], v[170:173], v[60:63]
	v_mfma_f32_16x16x32_bf16 v[44:47], v[154:157], v[186:189], v[44:47]
	v_mfma_f32_16x16x32_bf16 v[40:43], v[162:165], v[186:189], v[40:43]
	v_mfma_f32_16x16x32_bf16 v[28:31], v[154:157], v[194:197], v[28:31]
	v_mfma_f32_16x16x32_bf16 v[24:27], v[162:165], v[194:197], v[24:27]
	v_mfma_f32_16x16x32_bf16 v[12:15], v[154:157], v[202:205], v[12:15]
	v_mfma_f32_16x16x32_bf16 v[8:11], v[162:165], v[202:205], v[8:11]
	s_barrier
	s_add_u32 s36, s36, 0x100080
	s_addc_u32 s37, s37, 0
	s_add_i32 s3, s3, s41
	s_mov_b32 m0, s3
	v_lshl_add_u64 v[150:151], s[36:37], 0, v[134:135]
	global_load_lds_dwordx4 v[150:151], off
	s_add_i32 m0, s3, 0x2000
	v_lshl_add_u64 v[150:151], s[36:37], 0, v[136:137]
	global_load_lds_dwordx4 v[150:151], off
	s_waitcnt vmcnt(6)
	s_barrier
	v_mfma_f32_16x16x32_bf16 v[52:55], v[206:209], v[166:169], v[52:55]
	v_mfma_f32_16x16x32_bf16 v[48:51], v[218:221], v[166:169], v[48:51]
	v_mfma_f32_16x16x32_bf16 v[36:39], v[206:209], v[182:185], v[36:39]
	v_mfma_f32_16x16x32_bf16 v[32:35], v[218:221], v[182:185], v[32:35]
	v_mfma_f32_16x16x32_bf16 v[20:23], v[206:209], v[190:193], v[20:23]
	v_mfma_f32_16x16x32_bf16 v[16:19], v[218:221], v[190:193], v[16:19]
	v_mfma_f32_16x16x32_bf16 v[4:7], v[206:209], v[198:201], v[4:7]
	v_mfma_f32_16x16x32_bf16 v[0:3], v[218:221], v[198:201], v[0:3]
	v_mfma_f32_16x16x32_bf16 v[52:55], v[214:217], v[170:173], v[52:55]
	v_mfma_f32_16x16x32_bf16 v[48:51], v[222:225], v[170:173], v[48:51]
	v_mfma_f32_16x16x32_bf16 v[36:39], v[214:217], v[186:189], v[36:39]
	v_mfma_f32_16x16x32_bf16 v[32:35], v[222:225], v[186:189], v[32:35]
	v_mfma_f32_16x16x32_bf16 v[20:23], v[214:217], v[194:197], v[20:23]
	v_mfma_f32_16x16x32_bf16 v[16:19], v[222:225], v[194:197], v[16:19]
	v_mfma_f32_16x16x32_bf16 v[4:7], v[214:217], v[202:205], v[4:7]
	v_mfma_f32_16x16x32_bf16 v[0:3], v[222:225], v[202:205], v[0:3]
	s_add_u32 s34, s34, 0x100
	s_addc_u32 s35, s35, 0
	s_cmp_ge_u32 s89, s49
	s_cbranch_scc1 .Lrot_exit_out

.LBB0_640:
	s_add_i32 s89, s89, 2
	s_add_u32 s3, s22, s34
	ds_read_b128 v[150:153], v250
	ds_read_b128 v[154:157], v250 offset:1024
	ds_read_b128 v[158:161], v250 offset:2048
	ds_read_b128 v[162:165], v250 offset:3072
	s_addc_u32 s36, s23, s35
	s_add_u32 s3, s3, 0x100
	s_addc_u32 s36, s36, 0
	s_add_u32 s90, s83, s34
	s_addc_u32 s37, s84, s35
	s_cmp_eq_u32 s88, s34
	s_cselect_b32 s39, s11, s36
	s_cselect_b32 s38, s85, s3
	s_cselect_b32 s37, s86, s37
	s_cselect_b32 s36, s87, s90
	s_mov_b32 m0, s73
	v_lshl_add_u64 v[174:175], v[58:59], 0, s[34:35]
	ds_read_b128 v[166:169], v133
	ds_read_b128 v[170:173], v133 offset:1024
	ds_read_b128 v[182:185], v133 offset:2048
	ds_read_b128 v[186:189], v133 offset:3072
	ds_read_b128 v[190:193], v133 offset:4096
	ds_read_b128 v[194:197], v133 offset:5120
	ds_read_b128 v[198:201], v133 offset:6144
	ds_read_b128 v[202:205], v133 offset:7168
	global_load_lds_dwordx4 v[174:175], off
	s_mov_b32 m0, s74
	v_lshl_add_u64 v[174:175], v[146:147], 0, s[34:35]
	global_load_lds_dwordx4 v[174:175], off
	s_waitcnt lgkmcnt(8)
	s_barrier
	s_waitcnt lgkmcnt(0)
	v_mfma_f32_16x16x32_bf16 v[128:131], v[150:153], v[166:169], v[128:131]
	v_mfma_f32_16x16x32_bf16 v[124:127], v[158:161], v[166:169], v[124:127]
	v_mfma_f32_16x16x32_bf16 v[112:115], v[150:153], v[182:185], v[112:115]
	v_mfma_f32_16x16x32_bf16 v[108:111], v[158:161], v[182:185], v[108:111]
	v_mfma_f32_16x16x32_bf16 v[96:99], v[150:153], v[190:193], v[96:99]
	v_mfma_f32_16x16x32_bf16 v[92:95], v[158:161], v[190:193], v[92:95]
	v_mfma_f32_16x16x32_bf16 v[80:83], v[150:153], v[198:201], v[80:83]
	v_mfma_f32_16x16x32_bf16 v[76:79], v[158:161], v[198:201], v[76:79]
	v_mfma_f32_16x16x32_bf16 v[128:131], v[154:157], v[170:173], v[128:131]
	v_mfma_f32_16x16x32_bf16 v[124:127], v[162:165], v[170:173], v[124:127]
	v_mfma_f32_16x16x32_bf16 v[112:115], v[154:157], v[186:189], v[112:115]
	v_mfma_f32_16x16x32_bf16 v[108:111], v[162:165], v[186:189], v[108:111]
	v_mfma_f32_16x16x32_bf16 v[96:99], v[154:157], v[194:197], v[96:99]
	v_mfma_f32_16x16x32_bf16 v[92:95], v[162:165], v[194:197], v[92:95]
	v_mfma_f32_16x16x32_bf16 v[80:83], v[154:157], v[202:205], v[80:83]
	v_mfma_f32_16x16x32_bf16 v[76:79], v[162:165], v[202:205], v[76:79]
	s_barrier
	s_mov_b32 m0, s75
	v_lshl_add_u64 v[174:175], s[36:37], 0, v[134:135]
	ds_read_b128 v[206:209], v251
	ds_read_b128 v[214:217], v251 offset:1024
	ds_read_b128 v[218:221], v251 offset:2048
	ds_read_b128 v[222:225], v251 offset:3072
	global_load_lds_dwordx4 v[174:175], off
	s_mov_b32 m0, s76
	v_lshl_add_u64 v[226:227], s[36:37], 0, v[136:137]
	global_load_lds_dwordx4 v[226:227], off
	s_barrier
	s_waitcnt lgkmcnt(0)
	v_mfma_f32_16x16x32_bf16 v[120:123], v[206:209], v[166:169], v[120:123]
	v_mfma_f32_16x16x32_bf16 v[116:119], v[218:221], v[166:169], v[116:119]
	v_mfma_f32_16x16x32_bf16 v[104:107], v[206:209], v[182:185], v[104:107]
	v_mfma_f32_16x16x32_bf16 v[100:103], v[218:221], v[182:185], v[100:103]
	v_mfma_f32_16x16x32_bf16 v[88:91], v[206:209], v[190:193], v[88:91]
	v_mfma_f32_16x16x32_bf16 v[84:87], v[218:221], v[190:193], v[84:87]
	v_mfma_f32_16x16x32_bf16 v[72:75], v[206:209], v[198:201], v[72:75]
	v_mfma_f32_16x16x32_bf16 v[68:71], v[218:221], v[198:201], v[68:71]
	v_mfma_f32_16x16x32_bf16 v[120:123], v[214:217], v[170:173], v[120:123]
	v_mfma_f32_16x16x32_bf16 v[116:119], v[222:225], v[170:173], v[116:119]
	v_mfma_f32_16x16x32_bf16 v[104:107], v[214:217], v[186:189], v[104:107]
	v_mfma_f32_16x16x32_bf16 v[100:103], v[222:225], v[186:189], v[100:103]
	v_mfma_f32_16x16x32_bf16 v[88:91], v[214:217], v[194:197], v[88:91]
	v_mfma_f32_16x16x32_bf16 v[84:87], v[222:225], v[194:197], v[84:87]
	v_mfma_f32_16x16x32_bf16 v[72:75], v[214:217], v[202:205], v[72:75]
	v_mfma_f32_16x16x32_bf16 v[68:71], v[222:225], v[202:205], v[68:71]
	s_mov_b32 m0, s44
	v_lshl_add_u64 v[228:229], s[38:39], 0, v[134:135]
	s_barrier
	ds_read_b128 v[166:169], v133 offset:16384
	ds_read_b128 v[170:173], v133 offset:17408
	ds_read_b128 v[182:185], v133 offset:18432
	ds_read_b128 v[186:189], v133 offset:19456
	ds_read_b128 v[190:193], v133 offset:20480
	ds_read_b128 v[194:197], v133 offset:21504
	ds_read_b128 v[198:201], v133 offset:22528
	ds_read_b128 v[202:205], v133 offset:23552
	global_load_lds_dwordx4 v[228:229], off
	s_mov_b32 m0, s45
	v_lshl_add_u64 v[230:231], s[38:39], 0, v[136:137]
	global_load_lds_dwordx4 v[230:231], off
	s_barrier
	s_waitcnt lgkmcnt(0)
	v_mfma_f32_16x16x32_bf16 v[64:67], v[150:153], v[166:169], v[64:67]
	v_mfma_f32_16x16x32_bf16 v[60:63], v[158:161], v[166:169], v[60:63]
	v_mfma_f32_16x16x32_bf16 v[44:47], v[150:153], v[182:185], v[44:47]
	v_mfma_f32_16x16x32_bf16 v[40:43], v[158:161], v[182:185], v[40:43]
	v_mfma_f32_16x16x32_bf16 v[28:31], v[150:153], v[190:193], v[28:31]
	v_mfma_f32_16x16x32_bf16 v[24:27], v[158:161], v[190:193], v[24:27]
	v_mfma_f32_16x16x32_bf16 v[12:15], v[150:153], v[198:201], v[12:15]
	v_mfma_f32_16x16x32_bf16 v[8:11], v[158:161], v[198:201], v[8:11]
	v_mfma_f32_16x16x32_bf16 v[64:67], v[154:157], v[170:173], v[64:67]
	v_mfma_f32_16x16x32_bf16 v[60:63], v[162:165], v[170:173], v[60:63]
	v_mfma_f32_16x16x32_bf16 v[44:47], v[154:157], v[186:189], v[44:47]
	v_mfma_f32_16x16x32_bf16 v[40:43], v[162:165], v[186:189], v[40:43]
	v_mfma_f32_16x16x32_bf16 v[28:31], v[154:157], v[194:197], v[28:31]
	v_mfma_f32_16x16x32_bf16 v[24:27], v[162:165], v[194:197], v[24:27]
	v_mfma_f32_16x16x32_bf16 v[12:15], v[154:157], v[202:205], v[12:15]
	v_mfma_f32_16x16x32_bf16 v[8:11], v[162:165], v[202:205], v[8:11]
	s_barrier
	s_add_u32 s90, s36, 0x100000
	s_addc_u32 s91, s37, 0
	s_mov_b32 m0, s77
	v_lshl_add_u64 v[150:151], s[90:91], 0, v[134:135]
	global_load_lds_dwordx4 v[150:151], off
	s_mov_b32 m0, s78
	v_lshl_add_u64 v[150:151], s[90:91], 0, v[136:137]
	global_load_lds_dwordx4 v[150:151], off
	s_waitcnt vmcnt(6)
	s_barrier
	v_mfma_f32_16x16x32_bf16 v[52:55], v[206:209], v[166:169], v[52:55]
	v_mfma_f32_16x16x32_bf16 v[48:51], v[218:221], v[166:169], v[48:51]
	v_mfma_f32_16x16x32_bf16 v[36:39], v[206:209], v[182:185], v[36:39]
	v_mfma_f32_16x16x32_bf16 v[32:35], v[218:221], v[182:185], v[32:35]
	v_mfma_f32_16x16x32_bf16 v[20:23], v[206:209], v[190:193], v[20:23]
	v_mfma_f32_16x16x32_bf16 v[16:19], v[218:221], v[190:193], v[16:19]
	v_mfma_f32_16x16x32_bf16 v[4:7], v[206:209], v[198:201], v[4:7]
	v_mfma_f32_16x16x32_bf16 v[0:3], v[218:221], v[198:201], v[0:3]
	v_mfma_f32_16x16x32_bf16 v[52:55], v[214:217], v[170:173], v[52:55]
	v_mfma_f32_16x16x32_bf16 v[48:51], v[222:225], v[170:173], v[48:51]
	v_mfma_f32_16x16x32_bf16 v[36:39], v[214:217], v[186:189], v[36:39]
	v_mfma_f32_16x16x32_bf16 v[32:35], v[222:225], v[186:189], v[32:35]
	v_mfma_f32_16x16x32_bf16 v[20:23], v[214:217], v[194:197], v[20:23]
	v_mfma_f32_16x16x32_bf16 v[16:19], v[222:225], v[194:197], v[16:19]
	v_mfma_f32_16x16x32_bf16 v[4:7], v[214:217], v[202:205], v[4:7]
	v_mfma_f32_16x16x32_bf16 v[0:3], v[222:225], v[202:205], v[0:3]
	s_barrier
	ds_read_b128 v[150:153], v252
	ds_read_b128 v[154:157], v252 offset:1024
	ds_read_b128 v[158:161], v252 offset:2048
	ds_read_b128 v[162:165], v252 offset:3072
	s_add_u32 s38, s38, 0x100000
	s_addc_u32 s39, s39, 0
	s_mov_b32 m0, s46
	v_lshl_add_u64 v[206:207], s[38:39], 0, v[134:135]
	ds_read_b128 v[166:169], v133 offset:32768
	ds_read_b128 v[170:173], v133 offset:33792
	ds_read_b128 v[182:185], v133 offset:34816
	ds_read_b128 v[186:189], v133 offset:35840
	ds_read_b128 v[190:193], v133 offset:36864
	ds_read_b128 v[194:197], v133 offset:37888
	ds_read_b128 v[198:201], v133 offset:38912
	ds_read_b128 v[202:205], v133 offset:39936
	global_load_lds_dwordx4 v[206:207], off
	s_mov_b32 m0, s47
	v_lshl_add_u64 v[206:207], s[38:39], 0, v[136:137]
	global_load_lds_dwordx4 v[206:207], off
	s_waitcnt lgkmcnt(8)
	s_barrier
	s_waitcnt lgkmcnt(0)
	v_mfma_f32_16x16x32_bf16 v[128:131], v[150:153], v[166:169], v[128:131]
	v_mfma_f32_16x16x32_bf16 v[124:127], v[158:161], v[166:169], v[124:127]
	v_mfma_f32_16x16x32_bf16 v[112:115], v[150:153], v[182:185], v[112:115]
	v_mfma_f32_16x16x32_bf16 v[108:111], v[158:161], v[182:185], v[108:111]
	v_mfma_f32_16x16x32_bf16 v[96:99], v[150:153], v[190:193], v[96:99]
	v_mfma_f32_16x16x32_bf16 v[92:95], v[158:161], v[190:193], v[92:95]
	v_mfma_f32_16x16x32_bf16 v[80:83], v[150:153], v[198:201], v[80:83]
	v_mfma_f32_16x16x32_bf16 v[76:79], v[158:161], v[198:201], v[76:79]
	v_mfma_f32_16x16x32_bf16 v[128:131], v[154:157], v[170:173], v[128:131]
	v_mfma_f32_16x16x32_bf16 v[124:127], v[162:165], v[170:173], v[124:127]
	v_mfma_f32_16x16x32_bf16 v[112:115], v[154:157], v[186:189], v[112:115]
	v_mfma_f32_16x16x32_bf16 v[108:111], v[162:165], v[186:189], v[108:111]
	v_mfma_f32_16x16x32_bf16 v[96:99], v[154:157], v[194:197], v[96:99]
	v_mfma_f32_16x16x32_bf16 v[92:95], v[162:165], v[194:197], v[92:95]
	v_mfma_f32_16x16x32_bf16 v[80:83], v[154:157], v[202:205], v[80:83]
	v_mfma_f32_16x16x32_bf16 v[76:79], v[162:165], v[202:205], v[76:79]
	s_barrier
	s_add_i32 s3, 0, 0x1c000
	s_add_i32 s38, s79, s41
	v_lshl_add_u64 v[174:175], v[174:175], 0, s[16:17]
	s_mov_b32 m0, s38
	ds_read_b128 v[206:209], v253
	ds_read_b128 v[214:217], v253 offset:1024
	ds_read_b128 v[218:221], v253 offset:2048
	ds_read_b128 v[222:225], v253 offset:3072
	global_load_lds_dwordx4 v[174:175], off
	s_add_i32 m0, s38, 0x2000
	v_lshl_add_u64 v[174:175], v[226:227], 0, s[16:17]
	global_load_lds_dwordx4 v[174:175], off
	s_barrier
	s_waitcnt lgkmcnt(0)
	v_mfma_f32_16x16x32_bf16 v[120:123], v[206:209], v[166:169], v[120:123]
	v_mfma_f32_16x16x32_bf16 v[116:119], v[218:221], v[166:169], v[116:119]
	v_mfma_f32_16x16x32_bf16 v[104:107], v[206:209], v[182:185], v[104:107]
	v_mfma_f32_16x16x32_bf16 v[100:103], v[218:221], v[182:185], v[100:103]
	v_mfma_f32_16x16x32_bf16 v[88:91], v[206:209], v[190:193], v[88:91]
	v_mfma_f32_16x16x32_bf16 v[84:87], v[218:221], v[190:193], v[84:87]
	v_mfma_f32_16x16x32_bf16 v[72:75], v[206:209], v[198:201], v[72:75]
	v_mfma_f32_16x16x32_bf16 v[68:71], v[218:221], v[198:201], v[68:71]
	v_mfma_f32_16x16x32_bf16 v[120:123], v[214:217], v[170:173], v[120:123]
	v_mfma_f32_16x16x32_bf16 v[116:119], v[222:225], v[170:173], v[116:119]
	v_mfma_f32_16x16x32_bf16 v[104:107], v[214:217], v[186:189], v[104:107]
	v_mfma_f32_16x16x32_bf16 v[100:103], v[222:225], v[186:189], v[100:103]
	v_mfma_f32_16x16x32_bf16 v[88:91], v[214:217], v[194:197], v[88:91]
	v_mfma_f32_16x16x32_bf16 v[84:87], v[222:225], v[194:197], v[84:87]
	v_mfma_f32_16x16x32_bf16 v[72:75], v[214:217], v[202:205], v[72:75]
	v_mfma_f32_16x16x32_bf16 v[68:71], v[222:225], v[202:205], v[68:71]
	s_mov_b32 m0, s67
	v_lshl_add_u64 v[174:175], v[228:229], 0, s[16:17]
	s_barrier
	ds_read_b128 v[166:169], v133 offset:49152
	ds_read_b128 v[170:173], v133 offset:50176
	ds_read_b128 v[182:185], v133 offset:51200
	ds_read_b128 v[186:189], v133 offset:52224
	ds_read_b128 v[190:193], v133 offset:53248
	ds_read_b128 v[194:197], v133 offset:54272
	ds_read_b128 v[198:201], v133 offset:55296
	ds_read_b128 v[202:205], v133 offset:56320
	global_load_lds_dwordx4 v[174:175], off
	s_mov_b32 m0, s68
	v_lshl_add_u64 v[174:175], v[230:231], 0, s[16:17]
	global_load_lds_dwordx4 v[174:175], off
	s_barrier
	s_waitcnt lgkmcnt(0)
	v_mfma_f32_16x16x32_bf16 v[64:67], v[150:153], v[166:169], v[64:67]
	v_mfma_f32_16x16x32_bf16 v[60:63], v[158:161], v[166:169], v[60:63]
	v_mfma_f32_16x16x32_bf16 v[44:47], v[150:153], v[182:185], v[44:47]
	v_mfma_f32_16x16x32_bf16 v[40:43], v[158:161], v[182:185], v[40:43]
	v_mfma_f32_16x16x32_bf16 v[28:31], v[150:153], v[190:193], v[28:31]
	v_mfma_f32_16x16x32_bf16 v[24:27], v[158:161], v[190:193], v[24:27]
	v_mfma_f32_16x16x32_bf16 v[12:15], v[150:153], v[198:201], v[12:15]
	v_mfma_f32_16x16x32_bf16 v[8:11], v[158:161], v[198:201], v[8:11]
	v_mfma_f32_16x16x32_bf16 v[64:67], v[154:157], v[170:173], v[64:67]
	v_mfma_f32_16x16x32_bf16 v[60:63], v[162:165], v[170:173], v[60:63]
	v_mfma_f32_16x16x32_bf16 v[44:47], v[154:157], v[186:189], v[44:47]
	v_mfma_f32_16x16x32_bf16 v[40:43], v[162:165], v[186:189], v[40:43]
	v_mfma_f32_16x16x32_bf16 v[28:31], v[154:157], v[194:197], v[28:31]
	v_mfma_f32_16x16x32_bf16 v[24:27], v[162:165], v[194:197], v[24:27]
	v_mfma_f32_16x16x32_bf16 v[12:15], v[154:157], v[202:205], v[12:15]
	v_mfma_f32_16x16x32_bf16 v[8:11], v[162:165], v[202:205], v[8:11]
	s_barrier
	s_add_u32 s36, s36, 0x100080
	s_addc_u32 s37, s37, 0
	s_add_i32 s3, s3, s41
	s_mov_b32 m0, s3
	v_lshl_add_u64 v[150:151], s[36:37], 0, v[134:135]
	global_load_lds_dwordx4 v[150:151], off
	s_add_i32 m0, s3, 0x2000
	v_lshl_add_u64 v[150:151], s[36:37], 0, v[136:137]
	global_load_lds_dwordx4 v[150:151], off
	s_waitcnt vmcnt(6)
	s_barrier
	v_mfma_f32_16x16x32_bf16 v[52:55], v[206:209], v[166:169], v[52:55]
	v_mfma_f32_16x16x32_bf16 v[48:51], v[218:221], v[166:169], v[48:51]
	v_mfma_f32_16x16x32_bf16 v[36:39], v[206:209], v[182:185], v[36:39]
	v_mfma_f32_16x16x32_bf16 v[32:35], v[218:221], v[182:185], v[32:35]
	v_mfma_f32_16x16x32_bf16 v[20:23], v[206:209], v[190:193], v[20:23]
	v_mfma_f32_16x16x32_bf16 v[16:19], v[218:221], v[190:193], v[16:19]
	v_mfma_f32_16x16x32_bf16 v[4:7], v[206:209], v[198:201], v[4:7]
	v_mfma_f32_16x16x32_bf16 v[0:3], v[218:221], v[198:201], v[0:3]
	v_mfma_f32_16x16x32_bf16 v[52:55], v[214:217], v[170:173], v[52:55]
	v_mfma_f32_16x16x32_bf16 v[48:51], v[222:225], v[170:173], v[48:51]
	v_mfma_f32_16x16x32_bf16 v[36:39], v[214:217], v[186:189], v[36:39]
	v_mfma_f32_16x16x32_bf16 v[32:35], v[222:225], v[186:189], v[32:35]
	v_mfma_f32_16x16x32_bf16 v[20:23], v[214:217], v[194:197], v[20:23]
	v_mfma_f32_16x16x32_bf16 v[16:19], v[222:225], v[194:197], v[16:19]
	v_mfma_f32_16x16x32_bf16 v[4:7], v[214:217], v[202:205], v[4:7]
	v_mfma_f32_16x16x32_bf16 v[0:3], v[222:225], v[202:205], v[0:3]
	s_add_u32 s34, s34, 0x100
	s_addc_u32 s35, s35, 0
	s_cmp_ge_u32 s89, s49
	s_cbranch_scc0 .Lrot_out
